# v43 + vmcnt(8)/lgkmcnt(0) wait pairs in GEMM load segments merged into one s_waitcnt (16 instrs)
# baseline (speedup 1.0000x reference)
.LBB0_38:
	s_add_i32 s52, s20, 2
	s_add_u32 s18, s16, 0x100
	s_addc_u32 s19, s17, 0
	s_add_i32 s53, 0, 0x10000
	s_cmp_eq_u32 s9, s20
	s_cselect_b32 s23, s1, s19
	s_cselect_b32 s22, s0, s18
	s_cselect_b32 s21, s11, s51
	s_cselect_b32 s20, s10, s50
	s_add_i32 s54, 0, 0x14000
	v_add_u32_e32 v154, s53, v168
	v_add_u32_e32 v166, s54, v168
	ds_read_b128 v[142:145], v154
	ds_read_b128 v[146:149], v154 offset:1024
	ds_read_b128 v[150:153], v154 offset:2048
	ds_read_b128 v[154:157], v154 offset:3072
	ds_read_b128 v[158:161], v166
	ds_read_b128 v[162:165], v166 offset:1024
	ds_read_b128 v[172:175], v166 offset:2048
	ds_read_b128 v[176:179], v166 offset:3072
	v_lshl_add_u64 v[166:167], s[16:17], 0, v[138:139]
	s_add_i32 m0, s25, 0xc000
	ds_read_b128 v[180:183], v170
	ds_read_b128 v[184:187], v170 offset:1024
	ds_read_b128 v[188:191], v170 offset:2048
	ds_read_b128 v[192:195], v170 offset:3072
	ds_read_b128 v[196:199], v170 offset:4096
	ds_read_b128 v[200:203], v170 offset:5120
	ds_read_b128 v[204:207], v170 offset:6144
	ds_read_b128 v[208:211], v170 offset:7168
	global_load_lds_dwordx4 v[166:167], off
	v_lshl_add_u64 v[166:167], s[16:17], 0, v[140:141]
	s_add_i32 m0, s25, 0xe000
	s_nop 0
	global_load_lds_dwordx4 v[166:167], off
	s_waitcnt vmcnt(8) lgkmcnt(0)
	s_barrier
	v_mfma_f32_16x16x32_bf16 v[130:133], v[142:145], v[180:183], v[130:133]
	v_mfma_f32_16x16x32_bf16 v[126:129], v[150:153], v[180:183], v[126:129]
	v_mfma_f32_16x16x32_bf16 v[122:125], v[142:145], v[188:191], v[122:125]
	v_mfma_f32_16x16x32_bf16 v[118:121], v[150:153], v[188:191], v[118:121]
	v_mfma_f32_16x16x32_bf16 v[114:117], v[142:145], v[196:199], v[114:117]
	v_mfma_f32_16x16x32_bf16 v[110:113], v[150:153], v[196:199], v[110:113]
	v_mfma_f32_16x16x32_bf16 v[106:109], v[142:145], v[204:207], v[106:109]
	v_mfma_f32_16x16x32_bf16 v[102:105], v[150:153], v[204:207], v[102:105]
	v_mfma_f32_16x16x32_bf16 v[130:133], v[146:149], v[184:187], v[130:133]
	v_mfma_f32_16x16x32_bf16 v[126:129], v[154:157], v[184:187], v[126:129]
	v_mfma_f32_16x16x32_bf16 v[122:125], v[146:149], v[192:195], v[122:125]
	v_mfma_f32_16x16x32_bf16 v[118:121], v[154:157], v[192:195], v[118:121]
	v_mfma_f32_16x16x32_bf16 v[114:117], v[146:149], v[200:203], v[114:117]
	v_mfma_f32_16x16x32_bf16 v[110:113], v[154:157], v[200:203], v[110:113]
	v_mfma_f32_16x16x32_bf16 v[106:109], v[146:149], v[208:211], v[106:109]
	v_mfma_f32_16x16x32_bf16 v[102:105], v[154:157], v[208:211], v[102:105]
	v_mfma_f32_16x16x32_bf16 v[98:101], v[158:161], v[180:183], v[98:101]
	v_mfma_f32_16x16x32_bf16 v[94:97], v[172:175], v[180:183], v[94:97]
	v_mfma_f32_16x16x32_bf16 v[90:93], v[158:161], v[188:191], v[90:93]
	v_mfma_f32_16x16x32_bf16 v[86:89], v[172:175], v[188:191], v[86:89]
	v_mfma_f32_16x16x32_bf16 v[82:85], v[158:161], v[196:199], v[82:85]
	v_mfma_f32_16x16x32_bf16 v[78:81], v[172:175], v[196:199], v[78:81]
	v_mfma_f32_16x16x32_bf16 v[74:77], v[158:161], v[204:207], v[74:77]
	v_mfma_f32_16x16x32_bf16 v[70:73], v[172:175], v[204:207], v[70:73]
	v_mfma_f32_16x16x32_bf16 v[98:101], v[162:165], v[184:187], v[98:101]
	v_mfma_f32_16x16x32_bf16 v[94:97], v[176:179], v[184:187], v[94:97]
	v_mfma_f32_16x16x32_bf16 v[90:93], v[162:165], v[192:195], v[90:93]
	v_mfma_f32_16x16x32_bf16 v[86:89], v[176:179], v[192:195], v[86:89]
	v_mfma_f32_16x16x32_bf16 v[82:85], v[162:165], v[200:203], v[82:85]
	v_mfma_f32_16x16x32_bf16 v[78:81], v[176:179], v[200:203], v[78:81]
	v_mfma_f32_16x16x32_bf16 v[74:77], v[162:165], v[208:211], v[74:77]
	v_mfma_f32_16x16x32_bf16 v[70:73], v[176:179], v[208:211], v[70:73]
	s_barrier
	s_add_i32 s16, s53, s24
	v_lshl_add_u64 v[166:167], s[20:21], 0, v[0:1]
	s_mov_b32 m0, s16
	ds_read_b128 v[180:183], v170 offset:16384
	ds_read_b128 v[184:187], v170 offset:17408
	ds_read_b128 v[188:191], v170 offset:18432
	ds_read_b128 v[192:195], v170 offset:19456
	ds_read_b128 v[196:199], v170 offset:20480
	ds_read_b128 v[200:203], v170 offset:21504
	ds_read_b128 v[204:207], v170 offset:22528
	ds_read_b128 v[208:211], v170 offset:23552
	global_load_lds_dwordx4 v[166:167], off
	s_add_i32 m0, s16, 0x2000
	s_add_u32 s16, s20, 0xc0000
	v_lshl_add_u64 v[212:213], s[20:21], 0, v[136:137]
	s_addc_u32 s17, s21, 0
	s_add_i32 s53, s54, s24
	global_load_lds_dwordx4 v[212:213], off
	v_lshl_add_u64 v[214:215], s[16:17], 0, v[0:1]
	s_mov_b32 m0, s53
	v_lshl_add_u64 v[216:217], s[22:23], 0, v[134:135]
	global_load_lds_dwordx4 v[214:215], off
	v_lshl_add_u64 v[214:215], s[16:17], 0, v[136:137]
	s_add_i32 m0, s53, 0x2000
	s_nop 0
	global_load_lds_dwordx4 v[214:215], off
	v_lshl_add_u64 v[214:215], s[22:23], 0, v[14:15]
	s_mov_b32 m0, s25
	s_nop 0
	global_load_lds_dwordx4 v[214:215], off
	s_mov_b32 m0, s26
	s_nop 0
	global_load_lds_dwordx4 v[216:217], off
	s_waitcnt vmcnt(8) lgkmcnt(0)
	s_barrier
	v_mfma_f32_16x16x32_bf16 v[66:69], v[142:145], v[180:183], v[66:69]
	v_mfma_f32_16x16x32_bf16 v[62:65], v[150:153], v[180:183], v[62:65]
	v_mfma_f32_16x16x32_bf16 v[58:61], v[142:145], v[188:191], v[58:61]
	v_mfma_f32_16x16x32_bf16 v[54:57], v[150:153], v[188:191], v[54:57]
	v_mfma_f32_16x16x32_bf16 v[50:53], v[142:145], v[196:199], v[50:53]
	v_mfma_f32_16x16x32_bf16 v[46:49], v[150:153], v[196:199], v[46:49]
	v_mfma_f32_16x16x32_bf16 v[42:45], v[142:145], v[204:207], v[42:45]
	v_mfma_f32_16x16x32_bf16 v[38:41], v[150:153], v[204:207], v[38:41]
	v_mfma_f32_16x16x32_bf16 v[66:69], v[146:149], v[184:187], v[66:69]
	v_mfma_f32_16x16x32_bf16 v[62:65], v[154:157], v[184:187], v[62:65]
	v_mfma_f32_16x16x32_bf16 v[58:61], v[146:149], v[192:195], v[58:61]
	v_mfma_f32_16x16x32_bf16 v[54:57], v[154:157], v[192:195], v[54:57]
	v_mfma_f32_16x16x32_bf16 v[50:53], v[146:149], v[200:203], v[50:53]
	v_mfma_f32_16x16x32_bf16 v[46:49], v[154:157], v[200:203], v[46:49]
	v_mfma_f32_16x16x32_bf16 v[42:45], v[146:149], v[208:211], v[42:45]
	v_mfma_f32_16x16x32_bf16 v[38:41], v[154:157], v[208:211], v[38:41]
	v_mfma_f32_16x16x32_bf16 v[34:37], v[158:161], v[180:183], v[34:37]
	v_mfma_f32_16x16x32_bf16 v[30:33], v[172:175], v[180:183], v[30:33]
	v_mfma_f32_16x16x32_bf16 v[26:29], v[158:161], v[188:191], v[26:29]
	v_mfma_f32_16x16x32_bf16 v[22:25], v[172:175], v[188:191], v[22:25]
	v_mfma_f32_16x16x32_bf16 v[18:21], v[158:161], v[196:199], v[18:21]
	v_mfma_f32_16x16x32_bf16 v[10:13], v[172:175], v[196:199], v[10:13]
	v_mfma_f32_16x16x32_bf16 v[6:9], v[158:161], v[204:207], v[6:9]
	v_mfma_f32_16x16x32_bf16 v[2:5], v[172:175], v[204:207], v[2:5]
	v_mfma_f32_16x16x32_bf16 v[34:37], v[162:165], v[184:187], v[34:37]
	v_mfma_f32_16x16x32_bf16 v[30:33], v[176:179], v[184:187], v[30:33]
	v_mfma_f32_16x16x32_bf16 v[26:29], v[162:165], v[192:195], v[26:29]
	v_mfma_f32_16x16x32_bf16 v[22:25], v[176:179], v[192:195], v[22:25]
	v_mfma_f32_16x16x32_bf16 v[18:21], v[162:165], v[200:203], v[18:21]
	v_mfma_f32_16x16x32_bf16 v[10:13], v[176:179], v[200:203], v[10:13]
	v_mfma_f32_16x16x32_bf16 v[6:9], v[162:165], v[208:211], v[6:9]
	v_mfma_f32_16x16x32_bf16 v[2:5], v[176:179], v[208:211], v[2:5]
	s_barrier
	s_add_i32 s53, 0, 0x18000
	s_add_i32 s54, 0, 0x1c000
	v_add_u32_e32 v154, s53, v168
	v_add_u32_e32 v171, s54, v168
	ds_read_b128 v[142:145], v154
	ds_read_b128 v[146:149], v154 offset:1024
	ds_read_b128 v[150:153], v154 offset:2048
	ds_read_b128 v[154:157], v154 offset:3072
	ds_read_b128 v[158:161], v171
	ds_read_b128 v[162:165], v171 offset:1024
	ds_read_b128 v[172:175], v171 offset:2048
	ds_read_b128 v[176:179], v171 offset:3072
	s_add_u32 s16, s22, 0xc0000
	s_addc_u32 s17, s23, 0
	s_mov_b32 m0, s27
	v_lshl_add_u64 v[218:219], s[16:17], 0, v[14:15]
	ds_read_b128 v[180:183], v170 offset:32768
	ds_read_b128 v[184:187], v170 offset:33792
	ds_read_b128 v[188:191], v170 offset:34816
	ds_read_b128 v[192:195], v170 offset:35840
	ds_read_b128 v[196:199], v170 offset:36864
	ds_read_b128 v[200:203], v170 offset:37888
	ds_read_b128 v[204:207], v170 offset:38912
	ds_read_b128 v[208:211], v170 offset:39936
	global_load_lds_dwordx4 v[218:219], off
	v_lshl_add_u64 v[218:219], s[16:17], 0, v[134:135]
	s_mov_b32 m0, s33
	s_nop 0
	global_load_lds_dwordx4 v[218:219], off
	s_waitcnt vmcnt(8) lgkmcnt(0)
	s_barrier
	v_mfma_f32_16x16x32_bf16 v[130:133], v[142:145], v[180:183], v[130:133]
	v_mfma_f32_16x16x32_bf16 v[126:129], v[150:153], v[180:183], v[126:129]
	v_mfma_f32_16x16x32_bf16 v[122:125], v[142:145], v[188:191], v[122:125]
	v_mfma_f32_16x16x32_bf16 v[118:121], v[150:153], v[188:191], v[118:121]
	v_mfma_f32_16x16x32_bf16 v[114:117], v[142:145], v[196:199], v[114:117]
	v_mfma_f32_16x16x32_bf16 v[110:113], v[150:153], v[196:199], v[110:113]
	v_mfma_f32_16x16x32_bf16 v[106:109], v[142:145], v[204:207], v[106:109]
	v_mfma_f32_16x16x32_bf16 v[102:105], v[150:153], v[204:207], v[102:105]
	v_mfma_f32_16x16x32_bf16 v[130:133], v[146:149], v[184:187], v[130:133]
	v_mfma_f32_16x16x32_bf16 v[126:129], v[154:157], v[184:187], v[126:129]
	v_mfma_f32_16x16x32_bf16 v[122:125], v[146:149], v[192:195], v[122:125]
	v_mfma_f32_16x16x32_bf16 v[118:121], v[154:157], v[192:195], v[118:121]
	v_mfma_f32_16x16x32_bf16 v[114:117], v[146:149], v[200:203], v[114:117]
	v_mfma_f32_16x16x32_bf16 v[110:113], v[154:157], v[200:203], v[110:113]
	v_mfma_f32_16x16x32_bf16 v[106:109], v[146:149], v[208:211], v[106:109]
	v_mfma_f32_16x16x32_bf16 v[102:105], v[154:157], v[208:211], v[102:105]
	v_mfma_f32_16x16x32_bf16 v[98:101], v[158:161], v[180:183], v[98:101]
	v_mfma_f32_16x16x32_bf16 v[94:97], v[172:175], v[180:183], v[94:97]
	v_mfma_f32_16x16x32_bf16 v[90:93], v[158:161], v[188:191], v[90:93]
	v_mfma_f32_16x16x32_bf16 v[86:89], v[172:175], v[188:191], v[86:89]
	v_mfma_f32_16x16x32_bf16 v[82:85], v[158:161], v[196:199], v[82:85]
	v_mfma_f32_16x16x32_bf16 v[78:81], v[172:175], v[196:199], v[78:81]
	v_mfma_f32_16x16x32_bf16 v[74:77], v[158:161], v[204:207], v[74:77]
	v_mfma_f32_16x16x32_bf16 v[70:73], v[172:175], v[204:207], v[70:73]
	v_mfma_f32_16x16x32_bf16 v[98:101], v[162:165], v[184:187], v[98:101]
	v_mfma_f32_16x16x32_bf16 v[94:97], v[176:179], v[184:187], v[94:97]
	v_mfma_f32_16x16x32_bf16 v[90:93], v[162:165], v[192:195], v[90:93]
	v_mfma_f32_16x16x32_bf16 v[86:89], v[176:179], v[192:195], v[86:89]
	v_mfma_f32_16x16x32_bf16 v[82:85], v[162:165], v[200:203], v[82:85]
	v_mfma_f32_16x16x32_bf16 v[78:81], v[176:179], v[200:203], v[78:81]
	v_mfma_f32_16x16x32_bf16 v[74:77], v[162:165], v[208:211], v[74:77]
	v_mfma_f32_16x16x32_bf16 v[70:73], v[176:179], v[208:211], v[70:73]
	s_barrier
	s_add_i32 s16, s53, s24
	v_lshl_add_u64 v[166:167], v[166:167], 0, s[36:37]
	s_mov_b32 m0, s16
	ds_read_b128 v[180:183], v170 offset:49152
	ds_read_b128 v[184:187], v170 offset:50176
	ds_read_b128 v[188:191], v170 offset:51200
	ds_read_b128 v[192:195], v170 offset:52224
	ds_read_b128 v[196:199], v170 offset:53248
	ds_read_b128 v[200:203], v170 offset:54272
	ds_read_b128 v[204:207], v170 offset:55296
	ds_read_b128 v[208:211], v170 offset:56320
	global_load_lds_dwordx4 v[166:167], off
	s_add_i32 m0, s16, 0x2000
	s_add_u32 s16, s20, 0xc0080
	v_lshl_add_u64 v[166:167], v[212:213], 0, s[36:37]
	s_addc_u32 s17, s21, 0
	s_add_i32 s20, s54, s24
	global_load_lds_dwordx4 v[166:167], off
	v_lshl_add_u64 v[166:167], s[16:17], 0, v[0:1]
	s_mov_b32 m0, s20
	s_nop 0
	global_load_lds_dwordx4 v[166:167], off
	v_lshl_add_u64 v[166:167], s[16:17], 0, v[136:137]
	s_add_i32 m0, s20, 0x2000
	s_nop 0
	global_load_lds_dwordx4 v[166:167], off
	v_lshl_add_u64 v[166:167], v[214:215], 0, s[36:37]
	s_mov_b32 m0, s45
	s_nop 0
	global_load_lds_dwordx4 v[166:167], off
	v_lshl_add_u64 v[166:167], v[216:217], 0, s[36:37]
	s_mov_b32 m0, s46
	s_nop 0
	global_load_lds_dwordx4 v[166:167], off
	s_waitcnt vmcnt(8) lgkmcnt(0)
	s_barrier
	v_mfma_f32_16x16x32_bf16 v[66:69], v[142:145], v[180:183], v[66:69]
	v_mfma_f32_16x16x32_bf16 v[62:65], v[150:153], v[180:183], v[62:65]
	v_mfma_f32_16x16x32_bf16 v[58:61], v[142:145], v[188:191], v[58:61]
	v_mfma_f32_16x16x32_bf16 v[54:57], v[150:153], v[188:191], v[54:57]
	v_mfma_f32_16x16x32_bf16 v[50:53], v[142:145], v[196:199], v[50:53]
	v_mfma_f32_16x16x32_bf16 v[46:49], v[150:153], v[196:199], v[46:49]
	v_mfma_f32_16x16x32_bf16 v[42:45], v[142:145], v[204:207], v[42:45]
	v_mfma_f32_16x16x32_bf16 v[38:41], v[150:153], v[204:207], v[38:41]
	v_mfma_f32_16x16x32_bf16 v[66:69], v[146:149], v[184:187], v[66:69]
	v_mfma_f32_16x16x32_bf16 v[62:65], v[154:157], v[184:187], v[62:65]
	v_mfma_f32_16x16x32_bf16 v[58:61], v[146:149], v[192:195], v[58:61]
	v_mfma_f32_16x16x32_bf16 v[54:57], v[154:157], v[192:195], v[54:57]
	v_mfma_f32_16x16x32_bf16 v[50:53], v[146:149], v[200:203], v[50:53]
	v_mfma_f32_16x16x32_bf16 v[46:49], v[154:157], v[200:203], v[46:49]
	v_mfma_f32_16x16x32_bf16 v[42:45], v[146:149], v[208:211], v[42:45]
	v_mfma_f32_16x16x32_bf16 v[38:41], v[154:157], v[208:211], v[38:41]
	v_mfma_f32_16x16x32_bf16 v[34:37], v[158:161], v[180:183], v[34:37]
	v_mfma_f32_16x16x32_bf16 v[30:33], v[172:175], v[180:183], v[30:33]
	v_mfma_f32_16x16x32_bf16 v[26:29], v[158:161], v[188:191], v[26:29]
	v_mfma_f32_16x16x32_bf16 v[22:25], v[172:175], v[188:191], v[22:25]
	v_mfma_f32_16x16x32_bf16 v[18:21], v[158:161], v[196:199], v[18:21]
	v_mfma_f32_16x16x32_bf16 v[10:13], v[172:175], v[196:199], v[10:13]
	v_mfma_f32_16x16x32_bf16 v[6:9], v[158:161], v[204:207], v[6:9]
	v_mfma_f32_16x16x32_bf16 v[2:5], v[172:175], v[204:207], v[2:5]
	v_mfma_f32_16x16x32_bf16 v[34:37], v[162:165], v[184:187], v[34:37]
	v_mfma_f32_16x16x32_bf16 v[30:33], v[176:179], v[184:187], v[30:33]
	v_mfma_f32_16x16x32_bf16 v[26:29], v[162:165], v[192:195], v[26:29]
	v_mfma_f32_16x16x32_bf16 v[22:25], v[176:179], v[192:195], v[22:25]
	v_mfma_f32_16x16x32_bf16 v[18:21], v[162:165], v[200:203], v[18:21]
	v_mfma_f32_16x16x32_bf16 v[10:13], v[176:179], v[200:203], v[10:13]
	v_mfma_f32_16x16x32_bf16 v[6:9], v[162:165], v[208:211], v[6:9]
	v_mfma_f32_16x16x32_bf16 v[2:5], v[176:179], v[208:211], v[2:5]
	s_barrier
	s_add_u32 s50, s50, 0x100
	s_addc_u32 s51, s51, 0
	s_cmp_ge_i32 s52, s43
	s_mov_b64 s[16:17], s[18:19]
	s_mov_b32 s20, s52
	s_cbranch_scc0 .LBB0_38
	s_and_b64 vcc, exec, s[6:7]
	s_cbranch_vccz .LBB0_41
	s_barrier

.LBB0_164:
	s_add_u32 s24, s18, 0xfff80080
	s_addc_u32 s25, s19, -1
	s_add_i32 s52, 0, 0x10000
	s_cmp_eq_u32 s51, 28
	s_cselect_b32 s47, s9, s25
	s_cselect_b32 s46, s21, s24
	v_add_u32_e32 v6, s52, v172
	s_cselect_b32 s25, s1, s50
	s_cselect_b32 s24, s23, s29
	s_add_i32 s54, 0, 0x14000
	ds_read_b128 v[126:129], v6
	ds_read_b128 v[130:133], v6 offset:1024
	ds_read_b128 v[142:145], v6 offset:2048
	ds_read_b128 v[146:149], v6 offset:3072
	v_add_u32_e32 v6, s54, v172
	ds_read_b128 v[166:169], v6
	ds_read_b128 v[204:207], v6 offset:1024
	ds_read_b128 v[208:211], v6 offset:2048
	ds_read_b128 v[216:219], v6 offset:3072
	v_lshl_add_u64 v[6:7], s[18:19], 0, v[162:163]
	s_add_i32 m0, s79, 0xc000
	ds_read_b128 v[220:223], v198
	ds_read_b128 v[224:227], v198 offset:1024
	ds_read_b128 v[228:231], v198 offset:2048
	ds_read_b128 v[232:235], v198 offset:3072
	ds_read_b128 v[236:239], v198 offset:4096
	ds_read_b128 v[240:243], v198 offset:5120
	ds_read_b128 v[244:247], v198 offset:6144
	ds_read_b128 v[248:251], v198 offset:7168
	global_load_lds_dwordx4 v[6:7], off
	v_lshl_add_u64 v[6:7], s[18:19], 0, v[164:165]
	s_add_i32 m0, s79, 0xe000
	s_nop 0
	global_load_lds_dwordx4 v[6:7], off
	s_waitcnt vmcnt(8) lgkmcnt(0)
	s_barrier
	v_mfma_f32_16x16x32_bf16 v[138:141], v[126:129], v[220:223], v[138:141]
	v_mfma_f32_16x16x32_bf16 v[134:137], v[142:145], v[220:223], v[134:137]
	v_mfma_f32_16x16x32_bf16 v[122:125], v[126:129], v[228:231], v[122:125]
	v_mfma_f32_16x16x32_bf16 v[118:121], v[142:145], v[228:231], v[118:121]
	v_mfma_f32_16x16x32_bf16 v[106:109], v[126:129], v[236:239], v[106:109]
	v_mfma_f32_16x16x32_bf16 v[102:105], v[142:145], v[236:239], v[102:105]
	v_mfma_f32_16x16x32_bf16 v[90:93], v[126:129], v[244:247], v[90:93]
	v_mfma_f32_16x16x32_bf16 v[86:89], v[142:145], v[244:247], v[86:89]
	v_mfma_f32_16x16x32_bf16 v[138:141], v[130:133], v[224:227], v[138:141]
	v_mfma_f32_16x16x32_bf16 v[134:137], v[146:149], v[224:227], v[134:137]
	v_mfma_f32_16x16x32_bf16 v[122:125], v[130:133], v[232:235], v[122:125]
	v_mfma_f32_16x16x32_bf16 v[118:121], v[146:149], v[232:235], v[118:121]
	v_mfma_f32_16x16x32_bf16 v[106:109], v[130:133], v[240:243], v[106:109]
	v_mfma_f32_16x16x32_bf16 v[102:105], v[146:149], v[240:243], v[102:105]
	v_mfma_f32_16x16x32_bf16 v[90:93], v[130:133], v[248:251], v[90:93]
	v_mfma_f32_16x16x32_bf16 v[86:89], v[146:149], v[248:251], v[86:89]
	v_mfma_f32_16x16x32_bf16 v[114:117], v[166:169], v[220:223], v[114:117]
	v_mfma_f32_16x16x32_bf16 v[110:113], v[208:211], v[220:223], v[110:113]
	v_mfma_f32_16x16x32_bf16 v[98:101], v[166:169], v[228:231], v[98:101]
	v_mfma_f32_16x16x32_bf16 v[94:97], v[208:211], v[228:231], v[94:97]
	v_mfma_f32_16x16x32_bf16 v[82:85], v[166:169], v[236:239], v[82:85]
	v_mfma_f32_16x16x32_bf16 v[78:81], v[208:211], v[236:239], v[78:81]
	v_mfma_f32_16x16x32_bf16 v[66:69], v[166:169], v[244:247], v[66:69]
	v_mfma_f32_16x16x32_bf16 v[62:65], v[208:211], v[244:247], v[62:65]
	v_mfma_f32_16x16x32_bf16 v[114:117], v[204:207], v[224:227], v[114:117]
	v_mfma_f32_16x16x32_bf16 v[110:113], v[216:219], v[224:227], v[110:113]
	v_mfma_f32_16x16x32_bf16 v[98:101], v[204:207], v[232:235], v[98:101]
	v_mfma_f32_16x16x32_bf16 v[94:97], v[216:219], v[232:235], v[94:97]
	v_mfma_f32_16x16x32_bf16 v[82:85], v[204:207], v[240:243], v[82:85]
	v_mfma_f32_16x16x32_bf16 v[78:81], v[216:219], v[240:243], v[78:81]
	v_mfma_f32_16x16x32_bf16 v[66:69], v[204:207], v[248:251], v[66:69]
	v_mfma_f32_16x16x32_bf16 v[62:65], v[216:219], v[248:251], v[62:65]
	s_barrier
	s_add_i32 s52, s52, s33
	v_lshl_add_u64 v[170:171], s[24:25], 0, v[0:1]
	s_mov_b32 m0, s52
	ds_read_b128 v[220:223], v198 offset:16384
	ds_read_b128 v[224:227], v198 offset:17408
	ds_read_b128 v[228:231], v198 offset:18432
	ds_read_b128 v[232:235], v198 offset:19456
	ds_read_b128 v[236:239], v198 offset:20480
	ds_read_b128 v[240:243], v198 offset:21504
	ds_read_b128 v[244:247], v198 offset:22528
	ds_read_b128 v[248:251], v198 offset:23552
	global_load_lds_dwordx4 v[170:171], off
	s_add_i32 m0, s52, 0x2000
	s_add_u32 s52, s24, 0x80000
	v_lshl_add_u64 v[200:201], s[24:25], 0, v[154:155]
	s_addc_u32 s53, s25, 0
	s_add_i32 s54, s54, s33
	global_load_lds_dwordx4 v[200:201], off
	v_lshl_add_u64 v[6:7], s[52:53], 0, v[0:1]
	s_mov_b32 m0, s54
	v_lshl_add_u64 v[202:203], s[46:47], 0, v[150:151]
	global_load_lds_dwordx4 v[6:7], off
	v_lshl_add_u64 v[6:7], s[52:53], 0, v[154:155]
	s_add_i32 m0, s54, 0x2000
	v_lshl_add_u64 v[212:213], s[46:47], 0, v[152:153]
	global_load_lds_dwordx4 v[6:7], off
	s_mov_b32 m0, s79
	s_nop 0
	global_load_lds_dwordx4 v[202:203], off
	s_mov_b32 m0, s81
	s_nop 0
	global_load_lds_dwordx4 v[212:213], off
	s_waitcnt vmcnt(8) lgkmcnt(0)
	s_barrier
	v_mfma_f32_16x16x32_bf16 v[74:77], v[126:129], v[220:223], v[74:77]
	v_mfma_f32_16x16x32_bf16 v[70:73], v[142:145], v[220:223], v[70:73]
	v_mfma_f32_16x16x32_bf16 v[58:61], v[126:129], v[228:231], v[58:61]
	v_mfma_f32_16x16x32_bf16 v[54:57], v[142:145], v[228:231], v[54:57]
	v_mfma_f32_16x16x32_bf16 v[42:45], v[126:129], v[236:239], v[42:45]
	v_mfma_f32_16x16x32_bf16 v[38:41], v[142:145], v[236:239], v[38:41]
	v_mfma_f32_16x16x32_bf16 v[22:25], v[126:129], v[244:247], v[22:25]
	v_mfma_f32_16x16x32_bf16 v[18:21], v[142:145], v[244:247], v[18:21]
	v_mfma_f32_16x16x32_bf16 v[74:77], v[130:133], v[224:227], v[74:77]
	v_mfma_f32_16x16x32_bf16 v[70:73], v[146:149], v[224:227], v[70:73]
	v_mfma_f32_16x16x32_bf16 v[58:61], v[130:133], v[232:235], v[58:61]
	v_mfma_f32_16x16x32_bf16 v[54:57], v[146:149], v[232:235], v[54:57]
	v_mfma_f32_16x16x32_bf16 v[42:45], v[130:133], v[240:243], v[42:45]
	v_mfma_f32_16x16x32_bf16 v[38:41], v[146:149], v[240:243], v[38:41]
	v_mfma_f32_16x16x32_bf16 v[22:25], v[130:133], v[248:251], v[22:25]
	v_mfma_f32_16x16x32_bf16 v[18:21], v[146:149], v[248:251], v[18:21]
	v_mfma_f32_16x16x32_bf16 v[50:53], v[166:169], v[220:223], v[50:53]
	v_mfma_f32_16x16x32_bf16 v[46:49], v[208:211], v[220:223], v[46:49]
	v_mfma_f32_16x16x32_bf16 v[34:37], v[166:169], v[228:231], v[34:37]
	v_mfma_f32_16x16x32_bf16 v[30:33], v[208:211], v[228:231], v[30:33]
	v_mfma_f32_16x16x32_bf16 v[26:29], v[166:169], v[236:239], v[26:29]
	v_mfma_f32_16x16x32_bf16 v[2:5], v[208:211], v[236:239], v[2:5]
	v_mfma_f32_16x16x32_bf16 v[12:15], v[166:169], v[244:247], v[12:15]
	v_mfma_f32_16x16x32_bf16 v[6:9], v[208:211], v[244:247], v[8:11]
	v_mfma_f32_16x16x32_bf16 v[50:53], v[204:207], v[224:227], v[50:53]
	v_mfma_f32_16x16x32_bf16 v[46:49], v[216:219], v[224:227], v[46:49]
	v_mfma_f32_16x16x32_bf16 v[34:37], v[204:207], v[232:235], v[34:37]
	v_mfma_f32_16x16x32_bf16 v[30:33], v[216:219], v[232:235], v[30:33]
	v_mfma_f32_16x16x32_bf16 v[26:29], v[204:207], v[240:243], v[26:29]
	v_mfma_f32_16x16x32_bf16 v[2:5], v[216:219], v[240:243], v[2:5]
	v_mfma_f32_16x16x32_bf16 v[12:15], v[204:207], v[248:251], v[12:15]
	v_mfma_f32_16x16x32_bf16 v[6:9], v[216:219], v[248:251], v[6:9]
	s_barrier
	s_add_i32 s52, 0, 0x18000
	v_add_u32_e32 v10, s52, v172
	s_add_i32 s53, 0, 0x1c000
	ds_read_b128 v[126:129], v10
	ds_read_b128 v[130:133], v10 offset:1024
	ds_read_b128 v[142:145], v10 offset:2048
	ds_read_b128 v[146:149], v10 offset:3072
	v_add_u32_e32 v10, s53, v172
	ds_read_b128 v[166:169], v10
	ds_read_b128 v[204:207], v10 offset:1024
	ds_read_b128 v[208:211], v10 offset:2048
	ds_read_b128 v[216:219], v10 offset:3072
	s_add_u32 s46, s46, 0x80000
	s_addc_u32 s47, s47, 0
	s_mov_b32 m0, s82
	v_lshl_add_u64 v[10:11], s[46:47], 0, v[150:151]
	ds_read_b128 v[220:223], v198 offset:32768
	ds_read_b128 v[224:227], v198 offset:33792
	ds_read_b128 v[228:231], v198 offset:34816
	ds_read_b128 v[232:235], v198 offset:35840
	ds_read_b128 v[236:239], v198 offset:36864
	ds_read_b128 v[240:243], v198 offset:37888
	ds_read_b128 v[244:247], v198 offset:38912
	ds_read_b128 v[248:251], v198 offset:39936
	global_load_lds_dwordx4 v[10:11], off
	v_lshl_add_u64 v[10:11], s[46:47], 0, v[152:153]
	s_mov_b32 m0, s83
	s_nop 0
	global_load_lds_dwordx4 v[10:11], off
	s_waitcnt vmcnt(8) lgkmcnt(0)
	s_barrier
	v_mfma_f32_16x16x32_bf16 v[138:141], v[126:129], v[220:223], v[138:141]
	v_mfma_f32_16x16x32_bf16 v[134:137], v[142:145], v[220:223], v[134:137]
	v_mfma_f32_16x16x32_bf16 v[122:125], v[126:129], v[228:231], v[122:125]
	v_mfma_f32_16x16x32_bf16 v[118:121], v[142:145], v[228:231], v[118:121]
	v_mfma_f32_16x16x32_bf16 v[106:109], v[126:129], v[236:239], v[106:109]
	v_mfma_f32_16x16x32_bf16 v[102:105], v[142:145], v[236:239], v[102:105]
	v_mfma_f32_16x16x32_bf16 v[90:93], v[126:129], v[244:247], v[90:93]
	v_mfma_f32_16x16x32_bf16 v[86:89], v[142:145], v[244:247], v[86:89]
	v_mfma_f32_16x16x32_bf16 v[138:141], v[130:133], v[224:227], v[138:141]
	v_mfma_f32_16x16x32_bf16 v[134:137], v[146:149], v[224:227], v[134:137]
	v_mfma_f32_16x16x32_bf16 v[122:125], v[130:133], v[232:235], v[122:125]
	v_mfma_f32_16x16x32_bf16 v[118:121], v[146:149], v[232:235], v[118:121]
	v_mfma_f32_16x16x32_bf16 v[106:109], v[130:133], v[240:243], v[106:109]
	v_mfma_f32_16x16x32_bf16 v[102:105], v[146:149], v[240:243], v[102:105]
	v_mfma_f32_16x16x32_bf16 v[90:93], v[130:133], v[248:251], v[90:93]
	v_mfma_f32_16x16x32_bf16 v[86:89], v[146:149], v[248:251], v[86:89]
	v_mfma_f32_16x16x32_bf16 v[114:117], v[166:169], v[220:223], v[114:117]
	v_mfma_f32_16x16x32_bf16 v[110:113], v[208:211], v[220:223], v[110:113]
	v_mfma_f32_16x16x32_bf16 v[98:101], v[166:169], v[228:231], v[98:101]
	v_mfma_f32_16x16x32_bf16 v[94:97], v[208:211], v[228:231], v[94:97]
	v_mfma_f32_16x16x32_bf16 v[82:85], v[166:169], v[236:239], v[82:85]
	v_mfma_f32_16x16x32_bf16 v[78:81], v[208:211], v[236:239], v[78:81]
	v_mfma_f32_16x16x32_bf16 v[66:69], v[166:169], v[244:247], v[66:69]
	v_mfma_f32_16x16x32_bf16 v[62:65], v[208:211], v[244:247], v[62:65]
	v_mfma_f32_16x16x32_bf16 v[114:117], v[204:207], v[224:227], v[114:117]
	v_mfma_f32_16x16x32_bf16 v[110:113], v[216:219], v[224:227], v[110:113]
	v_mfma_f32_16x16x32_bf16 v[98:101], v[204:207], v[232:235], v[98:101]
	v_mfma_f32_16x16x32_bf16 v[94:97], v[216:219], v[232:235], v[94:97]
	v_mfma_f32_16x16x32_bf16 v[82:85], v[204:207], v[240:243], v[82:85]
	v_mfma_f32_16x16x32_bf16 v[78:81], v[216:219], v[240:243], v[78:81]
	v_mfma_f32_16x16x32_bf16 v[66:69], v[204:207], v[248:251], v[66:69]
	v_mfma_f32_16x16x32_bf16 v[62:65], v[216:219], v[248:251], v[62:65]
	s_barrier
	s_add_i32 s46, s52, s33
	v_lshl_add_u64 v[10:11], v[170:171], 0, s[36:37]
	s_mov_b32 m0, s46
	ds_read_b128 v[220:223], v198 offset:49152
	ds_read_b128 v[224:227], v198 offset:50176
	ds_read_b128 v[228:231], v198 offset:51200
	ds_read_b128 v[232:235], v198 offset:52224
	ds_read_b128 v[236:239], v198 offset:53248
	ds_read_b128 v[240:243], v198 offset:54272
	ds_read_b128 v[244:247], v198 offset:55296
	ds_read_b128 v[248:251], v198 offset:56320
	global_load_lds_dwordx4 v[10:11], off
	s_add_i32 m0, s46, 0x2000
	s_add_u32 s24, s24, 0x80080
	v_lshl_add_u64 v[10:11], v[200:201], 0, s[36:37]
	s_addc_u32 s25, s25, 0
	s_add_i32 s46, s53, s33
	global_load_lds_dwordx4 v[10:11], off
	v_lshl_add_u64 v[10:11], s[24:25], 0, v[0:1]
	s_mov_b32 m0, s46
	s_nop 0
	global_load_lds_dwordx4 v[10:11], off
	v_lshl_add_u64 v[10:11], s[24:25], 0, v[154:155]
	s_add_i32 m0, s46, 0x2000
	s_nop 0
	global_load_lds_dwordx4 v[10:11], off
	v_lshl_add_u64 v[10:11], v[202:203], 0, s[36:37]
	s_mov_b32 m0, s94
	s_nop 0
	global_load_lds_dwordx4 v[10:11], off
	v_lshl_add_u64 v[10:11], v[212:213], 0, s[36:37]
	s_mov_b32 m0, s95
	s_nop 0
	global_load_lds_dwordx4 v[10:11], off
	s_add_i32 s51, s51, 2
	s_add_u32 s18, s18, 0x100
	s_addc_u32 s19, s19, 0
	s_add_u32 s29, s29, 0x100
	s_addc_u32 s50, s50, 0
	s_cmp_gt_u32 s51, 29
	s_waitcnt vmcnt(8) lgkmcnt(0)
	s_barrier
	v_mfma_f32_16x16x32_bf16 v[74:77], v[126:129], v[220:223], v[74:77]
	v_mfma_f32_16x16x32_bf16 v[70:73], v[142:145], v[220:223], v[70:73]
	v_mfma_f32_16x16x32_bf16 v[58:61], v[126:129], v[228:231], v[58:61]
	v_mfma_f32_16x16x32_bf16 v[54:57], v[142:145], v[228:231], v[54:57]
	v_mfma_f32_16x16x32_bf16 v[42:45], v[126:129], v[236:239], v[42:45]
	v_mfma_f32_16x16x32_bf16 v[38:41], v[142:145], v[236:239], v[38:41]
	v_mfma_f32_16x16x32_bf16 v[22:25], v[126:129], v[244:247], v[22:25]
	v_mfma_f32_16x16x32_bf16 v[18:21], v[142:145], v[244:247], v[18:21]
	v_mfma_f32_16x16x32_bf16 v[74:77], v[130:133], v[224:227], v[74:77]
	v_mfma_f32_16x16x32_bf16 v[70:73], v[146:149], v[224:227], v[70:73]
	v_mfma_f32_16x16x32_bf16 v[58:61], v[130:133], v[232:235], v[58:61]
	v_mfma_f32_16x16x32_bf16 v[54:57], v[146:149], v[232:235], v[54:57]
	v_mfma_f32_16x16x32_bf16 v[42:45], v[130:133], v[240:243], v[42:45]
	v_mfma_f32_16x16x32_bf16 v[38:41], v[146:149], v[240:243], v[38:41]
	v_mfma_f32_16x16x32_bf16 v[22:25], v[130:133], v[248:251], v[22:25]
	v_mfma_f32_16x16x32_bf16 v[18:21], v[146:149], v[248:251], v[18:21]
	v_mfma_f32_16x16x32_bf16 v[50:53], v[166:169], v[220:223], v[50:53]
	v_mfma_f32_16x16x32_bf16 v[46:49], v[208:211], v[220:223], v[46:49]
	v_mfma_f32_16x16x32_bf16 v[34:37], v[166:169], v[228:231], v[34:37]
	v_mfma_f32_16x16x32_bf16 v[30:33], v[208:211], v[228:231], v[30:33]
	v_mfma_f32_16x16x32_bf16 v[26:29], v[166:169], v[236:239], v[26:29]
	v_mfma_f32_16x16x32_bf16 v[2:5], v[208:211], v[236:239], v[2:5]
	v_mfma_f32_16x16x32_bf16 v[10:13], v[166:169], v[244:247], v[12:15]
	v_mfma_f32_16x16x32_bf16 v[6:9], v[208:211], v[244:247], v[6:9]
	v_mfma_f32_16x16x32_bf16 v[50:53], v[204:207], v[224:227], v[50:53]
	v_mfma_f32_16x16x32_bf16 v[46:49], v[216:219], v[224:227], v[46:49]
	v_mfma_f32_16x16x32_bf16 v[34:37], v[204:207], v[232:235], v[34:37]
	v_mfma_f32_16x16x32_bf16 v[30:33], v[216:219], v[232:235], v[30:33]
	v_mfma_f32_16x16x32_bf16 v[26:29], v[204:207], v[240:243], v[26:29]
	v_mfma_f32_16x16x32_bf16 v[2:5], v[216:219], v[240:243], v[2:5]
	v_mfma_f32_16x16x32_bf16 v[12:15], v[204:207], v[248:251], v[10:13]
	v_mfma_f32_16x16x32_bf16 v[8:11], v[216:219], v[248:251], v[6:9]
	s_barrier
	s_cbranch_scc0 .LBB0_164
	s_and_b64 vcc, exec, s[10:11]
	s_cbranch_vccz .LBB0_167
	s_barrier

.LBB0_756:
	s_add_u32 s44, s42, 0xfff80080
	s_addc_u32 s45, s43, -1
	s_add_i32 s62, 0, 0x10000
	s_cmp_eq_u32 s61, 28
	s_cselect_b32 s47, s1, s45
	s_cselect_b32 s46, s21, s44
	v_add_u32_e32 v146, s62, v148
	s_cselect_b32 s45, s19, s51
	s_cselect_b32 s44, s27, s29
	s_add_i32 s64, 0, 0x14000
	ds_read_b128 v[138:141], v146
	ds_read_b128 v[142:145], v146 offset:1024
	ds_read_b128 v[154:157], v146 offset:2048
	ds_read_b128 v[158:161], v146 offset:3072
	v_add_u32_e32 v146, s64, v148
	ds_read_b128 v[162:165], v146
	ds_read_b128 v[166:169], v146 offset:1024
	ds_read_b128 v[170:173], v146 offset:2048
	ds_read_b128 v[174:177], v146 offset:3072
	v_lshl_add_u64 v[146:147], s[42:43], 0, v[134:135]
	s_add_i32 m0, s50, 0xc000
	ds_read_b128 v[178:181], v152
	ds_read_b128 v[182:185], v152 offset:1024
	ds_read_b128 v[186:189], v152 offset:2048
	ds_read_b128 v[190:193], v152 offset:3072
	ds_read_b128 v[194:197], v152 offset:4096
	ds_read_b128 v[198:201], v152 offset:5120
	ds_read_b128 v[202:205], v152 offset:6144
	ds_read_b128 v[206:209], v152 offset:7168
	global_load_lds_dwordx4 v[146:147], off
	v_lshl_add_u64 v[146:147], s[42:43], 0, v[136:137]
	s_add_i32 m0, s50, 0xe000
	s_nop 0
	global_load_lds_dwordx4 v[146:147], off
	s_waitcnt vmcnt(8) lgkmcnt(0)
	s_barrier
	v_mfma_f32_16x16x32_bf16 v[130:133], v[138:141], v[178:181], v[130:133]
	v_mfma_f32_16x16x32_bf16 v[126:129], v[154:157], v[178:181], v[126:129]
	v_mfma_f32_16x16x32_bf16 v[114:117], v[138:141], v[186:189], v[114:117]
	v_mfma_f32_16x16x32_bf16 v[110:113], v[154:157], v[186:189], v[110:113]
	v_mfma_f32_16x16x32_bf16 v[98:101], v[138:141], v[194:197], v[98:101]
	v_mfma_f32_16x16x32_bf16 v[94:97], v[154:157], v[194:197], v[94:97]
	v_mfma_f32_16x16x32_bf16 v[82:85], v[138:141], v[202:205], v[82:85]
	v_mfma_f32_16x16x32_bf16 v[78:81], v[154:157], v[202:205], v[78:81]
	v_mfma_f32_16x16x32_bf16 v[130:133], v[142:145], v[182:185], v[130:133]
	v_mfma_f32_16x16x32_bf16 v[126:129], v[158:161], v[182:185], v[126:129]
	v_mfma_f32_16x16x32_bf16 v[114:117], v[142:145], v[190:193], v[114:117]
	v_mfma_f32_16x16x32_bf16 v[110:113], v[158:161], v[190:193], v[110:113]
	v_mfma_f32_16x16x32_bf16 v[98:101], v[142:145], v[198:201], v[98:101]
	v_mfma_f32_16x16x32_bf16 v[94:97], v[158:161], v[198:201], v[94:97]
	v_mfma_f32_16x16x32_bf16 v[82:85], v[142:145], v[206:209], v[82:85]
	v_mfma_f32_16x16x32_bf16 v[78:81], v[158:161], v[206:209], v[78:81]
	v_mfma_f32_16x16x32_bf16 v[122:125], v[162:165], v[178:181], v[122:125]
	v_mfma_f32_16x16x32_bf16 v[118:121], v[170:173], v[178:181], v[118:121]
	v_mfma_f32_16x16x32_bf16 v[106:109], v[162:165], v[186:189], v[106:109]
	v_mfma_f32_16x16x32_bf16 v[102:105], v[170:173], v[186:189], v[102:105]
	v_mfma_f32_16x16x32_bf16 v[90:93], v[162:165], v[194:197], v[90:93]
	v_mfma_f32_16x16x32_bf16 v[86:89], v[170:173], v[194:197], v[86:89]
	v_mfma_f32_16x16x32_bf16 v[74:77], v[162:165], v[202:205], v[74:77]
	v_mfma_f32_16x16x32_bf16 v[70:73], v[170:173], v[202:205], v[70:73]
	v_mfma_f32_16x16x32_bf16 v[122:125], v[166:169], v[182:185], v[122:125]
	v_mfma_f32_16x16x32_bf16 v[118:121], v[174:177], v[182:185], v[118:121]
	v_mfma_f32_16x16x32_bf16 v[106:109], v[166:169], v[190:193], v[106:109]
	v_mfma_f32_16x16x32_bf16 v[102:105], v[174:177], v[190:193], v[102:105]
	v_mfma_f32_16x16x32_bf16 v[90:93], v[166:169], v[198:201], v[90:93]
	v_mfma_f32_16x16x32_bf16 v[86:89], v[174:177], v[198:201], v[86:89]
	v_mfma_f32_16x16x32_bf16 v[74:77], v[166:169], v[206:209], v[74:77]
	v_mfma_f32_16x16x32_bf16 v[70:73], v[174:177], v[206:209], v[70:73]
	s_barrier
	s_add_i32 s62, s62, s33
	v_lshl_add_u64 v[146:147], s[44:45], 0, v[0:1]
	s_mov_b32 m0, s62
	ds_read_b128 v[178:181], v152 offset:16384
	ds_read_b128 v[182:185], v152 offset:17408
	ds_read_b128 v[186:189], v152 offset:18432
	ds_read_b128 v[190:193], v152 offset:19456
	ds_read_b128 v[194:197], v152 offset:20480
	ds_read_b128 v[198:201], v152 offset:21504
	ds_read_b128 v[202:205], v152 offset:22528
	ds_read_b128 v[206:209], v152 offset:23552
	global_load_lds_dwordx4 v[146:147], off
	s_add_i32 m0, s62, 0x2000
	s_add_u32 s62, s44, 0x80000
	v_lshl_add_u64 v[210:211], s[44:45], 0, v[14:15]
	s_addc_u32 s63, s45, 0
	s_add_i32 s64, s64, s33
	global_load_lds_dwordx4 v[210:211], off
	v_lshl_add_u64 v[212:213], s[62:63], 0, v[0:1]
	s_mov_b32 m0, s64
	v_lshl_add_u64 v[214:215], s[46:47], 0, v[14:15]
	global_load_lds_dwordx4 v[212:213], off
	v_lshl_add_u64 v[212:213], s[62:63], 0, v[14:15]
	s_add_i32 m0, s64, 0x2000
	s_nop 0
	global_load_lds_dwordx4 v[212:213], off
	v_lshl_add_u64 v[212:213], s[46:47], 0, v[0:1]
	s_mov_b32 m0, s50
	s_nop 0
	global_load_lds_dwordx4 v[212:213], off
	s_mov_b32 m0, s52
	s_nop 0
	global_load_lds_dwordx4 v[214:215], off
	s_waitcnt vmcnt(8) lgkmcnt(0)
	s_barrier
	v_mfma_f32_16x16x32_bf16 v[66:69], v[138:141], v[178:181], v[66:69]
	v_mfma_f32_16x16x32_bf16 v[62:65], v[154:157], v[178:181], v[62:65]
	v_mfma_f32_16x16x32_bf16 v[50:53], v[138:141], v[186:189], v[50:53]
	v_mfma_f32_16x16x32_bf16 v[46:49], v[154:157], v[186:189], v[46:49]
	v_mfma_f32_16x16x32_bf16 v[34:37], v[138:141], v[194:197], v[34:37]
	v_mfma_f32_16x16x32_bf16 v[30:33], v[154:157], v[194:197], v[30:33]
	v_mfma_f32_16x16x32_bf16 v[18:21], v[138:141], v[202:205], v[18:21]
	v_mfma_f32_16x16x32_bf16 v[10:13], v[154:157], v[202:205], v[10:13]
	v_mfma_f32_16x16x32_bf16 v[66:69], v[142:145], v[182:185], v[66:69]
	v_mfma_f32_16x16x32_bf16 v[62:65], v[158:161], v[182:185], v[62:65]
	v_mfma_f32_16x16x32_bf16 v[50:53], v[142:145], v[190:193], v[50:53]
	v_mfma_f32_16x16x32_bf16 v[46:49], v[158:161], v[190:193], v[46:49]
	v_mfma_f32_16x16x32_bf16 v[34:37], v[142:145], v[198:201], v[34:37]
	v_mfma_f32_16x16x32_bf16 v[30:33], v[158:161], v[198:201], v[30:33]
	v_mfma_f32_16x16x32_bf16 v[18:21], v[142:145], v[206:209], v[18:21]
	v_mfma_f32_16x16x32_bf16 v[10:13], v[158:161], v[206:209], v[10:13]
	v_mfma_f32_16x16x32_bf16 v[58:61], v[162:165], v[178:181], v[58:61]
	v_mfma_f32_16x16x32_bf16 v[54:57], v[170:173], v[178:181], v[54:57]
	v_mfma_f32_16x16x32_bf16 v[42:45], v[162:165], v[186:189], v[42:45]
	v_mfma_f32_16x16x32_bf16 v[38:41], v[170:173], v[186:189], v[38:41]
	v_mfma_f32_16x16x32_bf16 v[26:29], v[162:165], v[194:197], v[26:29]
	v_mfma_f32_16x16x32_bf16 v[22:25], v[170:173], v[194:197], v[22:25]
	v_mfma_f32_16x16x32_bf16 v[6:9], v[162:165], v[202:205], v[6:9]
	v_mfma_f32_16x16x32_bf16 v[2:5], v[170:173], v[202:205], v[2:5]
	v_mfma_f32_16x16x32_bf16 v[58:61], v[166:169], v[182:185], v[58:61]
	v_mfma_f32_16x16x32_bf16 v[54:57], v[174:177], v[182:185], v[54:57]
	v_mfma_f32_16x16x32_bf16 v[42:45], v[166:169], v[190:193], v[42:45]
	v_mfma_f32_16x16x32_bf16 v[38:41], v[174:177], v[190:193], v[38:41]
	v_mfma_f32_16x16x32_bf16 v[26:29], v[166:169], v[198:201], v[26:29]
	v_mfma_f32_16x16x32_bf16 v[22:25], v[174:177], v[198:201], v[22:25]
	v_mfma_f32_16x16x32_bf16 v[6:9], v[166:169], v[206:209], v[6:9]
	v_mfma_f32_16x16x32_bf16 v[2:5], v[174:177], v[206:209], v[2:5]
	s_barrier
	s_add_i32 s62, 0, 0x18000
	s_add_i32 s63, 0, 0x1c000
	v_add_u32_e32 v158, s62, v148
	v_add_u32_e32 v174, s63, v148
	ds_read_b128 v[138:141], v158
	ds_read_b128 v[142:145], v158 offset:1024
	ds_read_b128 v[154:157], v158 offset:2048
	ds_read_b128 v[158:161], v158 offset:3072
	ds_read_b128 v[162:165], v174
	ds_read_b128 v[166:169], v174 offset:1024
	ds_read_b128 v[170:173], v174 offset:2048
	ds_read_b128 v[174:177], v174 offset:3072
	s_add_u32 s46, s46, 0x80000
	s_addc_u32 s47, s47, 0
	s_mov_b32 m0, s53
	v_lshl_add_u64 v[216:217], s[46:47], 0, v[0:1]
	ds_read_b128 v[178:181], v152 offset:32768
	ds_read_b128 v[182:185], v152 offset:33792
	ds_read_b128 v[186:189], v152 offset:34816
	ds_read_b128 v[190:193], v152 offset:35840
	ds_read_b128 v[194:197], v152 offset:36864
	ds_read_b128 v[198:201], v152 offset:37888
	ds_read_b128 v[202:205], v152 offset:38912
	ds_read_b128 v[206:209], v152 offset:39936
	global_load_lds_dwordx4 v[216:217], off
	v_lshl_add_u64 v[216:217], s[46:47], 0, v[14:15]
	s_mov_b32 m0, s54
	s_nop 0
	global_load_lds_dwordx4 v[216:217], off
	s_waitcnt vmcnt(8) lgkmcnt(0)
	s_barrier
	v_mfma_f32_16x16x32_bf16 v[130:133], v[138:141], v[178:181], v[130:133]
	v_mfma_f32_16x16x32_bf16 v[126:129], v[154:157], v[178:181], v[126:129]
	v_mfma_f32_16x16x32_bf16 v[114:117], v[138:141], v[186:189], v[114:117]
	v_mfma_f32_16x16x32_bf16 v[110:113], v[154:157], v[186:189], v[110:113]
	v_mfma_f32_16x16x32_bf16 v[98:101], v[138:141], v[194:197], v[98:101]
	v_mfma_f32_16x16x32_bf16 v[94:97], v[154:157], v[194:197], v[94:97]
	v_mfma_f32_16x16x32_bf16 v[82:85], v[138:141], v[202:205], v[82:85]
	v_mfma_f32_16x16x32_bf16 v[78:81], v[154:157], v[202:205], v[78:81]
	v_mfma_f32_16x16x32_bf16 v[130:133], v[142:145], v[182:185], v[130:133]
	v_mfma_f32_16x16x32_bf16 v[126:129], v[158:161], v[182:185], v[126:129]
	v_mfma_f32_16x16x32_bf16 v[114:117], v[142:145], v[190:193], v[114:117]
	v_mfma_f32_16x16x32_bf16 v[110:113], v[158:161], v[190:193], v[110:113]
	v_mfma_f32_16x16x32_bf16 v[98:101], v[142:145], v[198:201], v[98:101]
	v_mfma_f32_16x16x32_bf16 v[94:97], v[158:161], v[198:201], v[94:97]
	v_mfma_f32_16x16x32_bf16 v[82:85], v[142:145], v[206:209], v[82:85]
	v_mfma_f32_16x16x32_bf16 v[78:81], v[158:161], v[206:209], v[78:81]
	v_mfma_f32_16x16x32_bf16 v[122:125], v[162:165], v[178:181], v[122:125]
	v_mfma_f32_16x16x32_bf16 v[118:121], v[170:173], v[178:181], v[118:121]
	v_mfma_f32_16x16x32_bf16 v[106:109], v[162:165], v[186:189], v[106:109]
	v_mfma_f32_16x16x32_bf16 v[102:105], v[170:173], v[186:189], v[102:105]
	v_mfma_f32_16x16x32_bf16 v[90:93], v[162:165], v[194:197], v[90:93]
	v_mfma_f32_16x16x32_bf16 v[86:89], v[170:173], v[194:197], v[86:89]
	v_mfma_f32_16x16x32_bf16 v[74:77], v[162:165], v[202:205], v[74:77]
	v_mfma_f32_16x16x32_bf16 v[70:73], v[170:173], v[202:205], v[70:73]
	v_mfma_f32_16x16x32_bf16 v[122:125], v[166:169], v[182:185], v[122:125]
	v_mfma_f32_16x16x32_bf16 v[118:121], v[174:177], v[182:185], v[118:121]
	v_mfma_f32_16x16x32_bf16 v[106:109], v[166:169], v[190:193], v[106:109]
	v_mfma_f32_16x16x32_bf16 v[102:105], v[174:177], v[190:193], v[102:105]
	v_mfma_f32_16x16x32_bf16 v[90:93], v[166:169], v[198:201], v[90:93]
	v_mfma_f32_16x16x32_bf16 v[86:89], v[174:177], v[198:201], v[86:89]
	v_mfma_f32_16x16x32_bf16 v[74:77], v[166:169], v[206:209], v[74:77]
	v_mfma_f32_16x16x32_bf16 v[70:73], v[174:177], v[206:209], v[70:73]
	s_barrier
	s_add_i32 s46, s62, s33
	v_lshl_add_u64 v[146:147], v[146:147], 0, s[36:37]
	s_mov_b32 m0, s46
	ds_read_b128 v[178:181], v152 offset:49152
	ds_read_b128 v[182:185], v152 offset:50176
	ds_read_b128 v[186:189], v152 offset:51200
	ds_read_b128 v[190:193], v152 offset:52224
	ds_read_b128 v[194:197], v152 offset:53248
	ds_read_b128 v[198:201], v152 offset:54272
	ds_read_b128 v[202:205], v152 offset:55296
	ds_read_b128 v[206:209], v152 offset:56320
	global_load_lds_dwordx4 v[146:147], off
	s_add_i32 m0, s46, 0x2000
	s_add_u32 s44, s44, 0x80080
	v_lshl_add_u64 v[146:147], v[210:211], 0, s[36:37]
	s_addc_u32 s45, s45, 0
	s_add_i32 s46, s63, s33
	global_load_lds_dwordx4 v[146:147], off
	v_lshl_add_u64 v[146:147], s[44:45], 0, v[0:1]
	s_mov_b32 m0, s46
	s_nop 0
	global_load_lds_dwordx4 v[146:147], off
	v_lshl_add_u64 v[146:147], s[44:45], 0, v[14:15]
	s_add_i32 m0, s46, 0x2000
	s_nop 0
	global_load_lds_dwordx4 v[146:147], off
	v_lshl_add_u64 v[146:147], v[212:213], 0, s[36:37]
	s_mov_b32 m0, s56
	s_nop 0
	global_load_lds_dwordx4 v[146:147], off
	v_lshl_add_u64 v[146:147], v[214:215], 0, s[36:37]
	s_mov_b32 m0, s57
	s_nop 0
	global_load_lds_dwordx4 v[146:147], off
	s_add_i32 s61, s61, 2
	s_add_u32 s42, s42, 0x100
	s_addc_u32 s43, s43, 0
	s_add_u32 s29, s29, 0x100
	s_addc_u32 s51, s51, 0
	s_cmp_gt_u32 s61, 29
	s_waitcnt vmcnt(8) lgkmcnt(0)
	s_barrier
	v_mfma_f32_16x16x32_bf16 v[66:69], v[138:141], v[178:181], v[66:69]
	v_mfma_f32_16x16x32_bf16 v[62:65], v[154:157], v[178:181], v[62:65]
	v_mfma_f32_16x16x32_bf16 v[50:53], v[138:141], v[186:189], v[50:53]
	v_mfma_f32_16x16x32_bf16 v[46:49], v[154:157], v[186:189], v[46:49]
	v_mfma_f32_16x16x32_bf16 v[34:37], v[138:141], v[194:197], v[34:37]
	v_mfma_f32_16x16x32_bf16 v[30:33], v[154:157], v[194:197], v[30:33]
	v_mfma_f32_16x16x32_bf16 v[18:21], v[138:141], v[202:205], v[18:21]
	v_mfma_f32_16x16x32_bf16 v[10:13], v[154:157], v[202:205], v[10:13]
	v_mfma_f32_16x16x32_bf16 v[66:69], v[142:145], v[182:185], v[66:69]
	v_mfma_f32_16x16x32_bf16 v[62:65], v[158:161], v[182:185], v[62:65]
	v_mfma_f32_16x16x32_bf16 v[50:53], v[142:145], v[190:193], v[50:53]
	v_mfma_f32_16x16x32_bf16 v[46:49], v[158:161], v[190:193], v[46:49]
	v_mfma_f32_16x16x32_bf16 v[34:37], v[142:145], v[198:201], v[34:37]
	v_mfma_f32_16x16x32_bf16 v[30:33], v[158:161], v[198:201], v[30:33]
	v_mfma_f32_16x16x32_bf16 v[18:21], v[142:145], v[206:209], v[18:21]
	v_mfma_f32_16x16x32_bf16 v[10:13], v[158:161], v[206:209], v[10:13]
	v_mfma_f32_16x16x32_bf16 v[58:61], v[162:165], v[178:181], v[58:61]
	v_mfma_f32_16x16x32_bf16 v[54:57], v[170:173], v[178:181], v[54:57]
	v_mfma_f32_16x16x32_bf16 v[42:45], v[162:165], v[186:189], v[42:45]
	v_mfma_f32_16x16x32_bf16 v[38:41], v[170:173], v[186:189], v[38:41]
	v_mfma_f32_16x16x32_bf16 v[26:29], v[162:165], v[194:197], v[26:29]
	v_mfma_f32_16x16x32_bf16 v[22:25], v[170:173], v[194:197], v[22:25]
	v_mfma_f32_16x16x32_bf16 v[6:9], v[162:165], v[202:205], v[6:9]
	v_mfma_f32_16x16x32_bf16 v[2:5], v[170:173], v[202:205], v[2:5]
	v_mfma_f32_16x16x32_bf16 v[58:61], v[166:169], v[182:185], v[58:61]
	v_mfma_f32_16x16x32_bf16 v[54:57], v[174:177], v[182:185], v[54:57]
	v_mfma_f32_16x16x32_bf16 v[42:45], v[166:169], v[190:193], v[42:45]
	v_mfma_f32_16x16x32_bf16 v[38:41], v[174:177], v[190:193], v[38:41]
	v_mfma_f32_16x16x32_bf16 v[26:29], v[166:169], v[198:201], v[26:29]
	v_mfma_f32_16x16x32_bf16 v[22:25], v[174:177], v[198:201], v[22:25]
	v_mfma_f32_16x16x32_bf16 v[6:9], v[166:169], v[206:209], v[6:9]
	v_mfma_f32_16x16x32_bf16 v[2:5], v[174:177], v[206:209], v[2:5]
	s_barrier
	s_cbranch_scc0 .LBB0_756
	s_and_b64 vcc, exec, s[10:11]
	s_cbranch_vccz .LBB0_759
	s_barrier

.LBB0_878:
	s_add_u32 s20, s8, 0xfff80080
	s_addc_u32 s21, s9, -1
	s_add_i32 s53, 0, 0x10000
	s_cmp_eq_u32 s52, 28
	s_cselect_b32 s23, s7, s21
	s_cselect_b32 s22, s25, s20
	v_add_u32_e32 v6, s53, v170
	s_cselect_b32 s21, s5, s51
	s_cselect_b32 s20, s47, s50
	s_add_i32 s54, 0, 0x14000
	ds_read_b128 v[126:129], v6
	ds_read_b128 v[130:133], v6 offset:1024
	ds_read_b128 v[142:145], v6 offset:2048
	ds_read_b128 v[146:149], v6 offset:3072
	v_add_u32_e32 v6, s54, v170
	ds_read_b128 v[164:167], v6
	ds_read_b128 v[204:207], v6 offset:1024
	ds_read_b128 v[208:211], v6 offset:2048
	ds_read_b128 v[216:219], v6 offset:3072
	v_lshl_add_u64 v[6:7], s[8:9], 0, v[160:161]
	s_add_i32 m0, s38, 0xc000
	ds_read_b128 v[220:223], v196
	ds_read_b128 v[224:227], v196 offset:1024
	ds_read_b128 v[228:231], v196 offset:2048
	ds_read_b128 v[232:235], v196 offset:3072
	ds_read_b128 v[236:239], v196 offset:4096
	ds_read_b128 v[240:243], v196 offset:5120
	ds_read_b128 v[244:247], v196 offset:6144
	ds_read_b128 v[248:251], v196 offset:7168
	global_load_lds_dwordx4 v[6:7], off
	v_lshl_add_u64 v[6:7], s[8:9], 0, v[162:163]
	s_add_i32 m0, s38, 0xe000
	s_nop 0
	global_load_lds_dwordx4 v[6:7], off
	s_waitcnt vmcnt(8) lgkmcnt(0)
	s_barrier
	v_mfma_f32_16x16x32_bf16 v[138:141], v[126:129], v[220:223], v[138:141]
	v_mfma_f32_16x16x32_bf16 v[134:137], v[142:145], v[220:223], v[134:137]
	v_mfma_f32_16x16x32_bf16 v[122:125], v[126:129], v[228:231], v[122:125]
	v_mfma_f32_16x16x32_bf16 v[118:121], v[142:145], v[228:231], v[118:121]
	v_mfma_f32_16x16x32_bf16 v[106:109], v[126:129], v[236:239], v[106:109]
	v_mfma_f32_16x16x32_bf16 v[102:105], v[142:145], v[236:239], v[102:105]
	v_mfma_f32_16x16x32_bf16 v[90:93], v[126:129], v[244:247], v[90:93]
	v_mfma_f32_16x16x32_bf16 v[86:89], v[142:145], v[244:247], v[86:89]
	v_mfma_f32_16x16x32_bf16 v[138:141], v[130:133], v[224:227], v[138:141]
	v_mfma_f32_16x16x32_bf16 v[134:137], v[146:149], v[224:227], v[134:137]
	v_mfma_f32_16x16x32_bf16 v[122:125], v[130:133], v[232:235], v[122:125]
	v_mfma_f32_16x16x32_bf16 v[118:121], v[146:149], v[232:235], v[118:121]
	v_mfma_f32_16x16x32_bf16 v[106:109], v[130:133], v[240:243], v[106:109]
	v_mfma_f32_16x16x32_bf16 v[102:105], v[146:149], v[240:243], v[102:105]
	v_mfma_f32_16x16x32_bf16 v[90:93], v[130:133], v[248:251], v[90:93]
	v_mfma_f32_16x16x32_bf16 v[86:89], v[146:149], v[248:251], v[86:89]
	v_mfma_f32_16x16x32_bf16 v[114:117], v[164:167], v[220:223], v[114:117]
	v_mfma_f32_16x16x32_bf16 v[110:113], v[208:211], v[220:223], v[110:113]
	v_mfma_f32_16x16x32_bf16 v[98:101], v[164:167], v[228:231], v[98:101]
	v_mfma_f32_16x16x32_bf16 v[94:97], v[208:211], v[228:231], v[94:97]
	v_mfma_f32_16x16x32_bf16 v[82:85], v[164:167], v[236:239], v[82:85]
	v_mfma_f32_16x16x32_bf16 v[78:81], v[208:211], v[236:239], v[78:81]
	v_mfma_f32_16x16x32_bf16 v[66:69], v[164:167], v[244:247], v[66:69]
	v_mfma_f32_16x16x32_bf16 v[62:65], v[208:211], v[244:247], v[62:65]
	v_mfma_f32_16x16x32_bf16 v[114:117], v[204:207], v[224:227], v[114:117]
	v_mfma_f32_16x16x32_bf16 v[110:113], v[216:219], v[224:227], v[110:113]
	v_mfma_f32_16x16x32_bf16 v[98:101], v[204:207], v[232:235], v[98:101]
	v_mfma_f32_16x16x32_bf16 v[94:97], v[216:219], v[232:235], v[94:97]
	v_mfma_f32_16x16x32_bf16 v[82:85], v[204:207], v[240:243], v[82:85]
	v_mfma_f32_16x16x32_bf16 v[78:81], v[216:219], v[240:243], v[78:81]
	v_mfma_f32_16x16x32_bf16 v[66:69], v[204:207], v[248:251], v[66:69]
	v_mfma_f32_16x16x32_bf16 v[62:65], v[216:219], v[248:251], v[62:65]
	s_barrier
	s_add_i32 s53, s53, s17
	v_lshl_add_u64 v[168:169], s[20:21], 0, v[0:1]
	s_mov_b32 m0, s53
	ds_read_b128 v[220:223], v196 offset:16384
	ds_read_b128 v[224:227], v196 offset:17408
	ds_read_b128 v[228:231], v196 offset:18432
	ds_read_b128 v[232:235], v196 offset:19456
	ds_read_b128 v[236:239], v196 offset:20480
	ds_read_b128 v[240:243], v196 offset:21504
	ds_read_b128 v[244:247], v196 offset:22528
	ds_read_b128 v[248:251], v196 offset:23552
	global_load_lds_dwordx4 v[168:169], off
	s_add_i32 m0, s53, 0x2000
	s_add_u32 s56, s20, 0x80000
	v_lshl_add_u64 v[198:199], s[20:21], 0, v[154:155]
	s_addc_u32 s57, s21, 0
	s_add_i32 s53, s54, s17
	global_load_lds_dwordx4 v[198:199], off
	v_lshl_add_u64 v[6:7], s[56:57], 0, v[0:1]
	s_mov_b32 m0, s53
	v_lshl_add_u64 v[200:201], s[22:23], 0, v[150:151]
	global_load_lds_dwordx4 v[6:7], off
	v_lshl_add_u64 v[6:7], s[56:57], 0, v[154:155]
	s_add_i32 m0, s53, 0x2000
	v_lshl_add_u64 v[202:203], s[22:23], 0, v[152:153]
	global_load_lds_dwordx4 v[6:7], off
	s_mov_b32 m0, s38
	s_nop 0
	global_load_lds_dwordx4 v[200:201], off
	s_mov_b32 m0, s39
	s_nop 0
	global_load_lds_dwordx4 v[202:203], off
	s_waitcnt vmcnt(8) lgkmcnt(0)
	s_barrier
	v_mfma_f32_16x16x32_bf16 v[74:77], v[126:129], v[220:223], v[74:77]
	v_mfma_f32_16x16x32_bf16 v[70:73], v[142:145], v[220:223], v[70:73]
	v_mfma_f32_16x16x32_bf16 v[58:61], v[126:129], v[228:231], v[58:61]
	v_mfma_f32_16x16x32_bf16 v[54:57], v[142:145], v[228:231], v[54:57]
	v_mfma_f32_16x16x32_bf16 v[42:45], v[126:129], v[236:239], v[42:45]
	v_mfma_f32_16x16x32_bf16 v[38:41], v[142:145], v[236:239], v[38:41]
	v_mfma_f32_16x16x32_bf16 v[22:25], v[126:129], v[244:247], v[22:25]
	v_mfma_f32_16x16x32_bf16 v[18:21], v[142:145], v[244:247], v[18:21]
	v_mfma_f32_16x16x32_bf16 v[74:77], v[130:133], v[224:227], v[74:77]
	v_mfma_f32_16x16x32_bf16 v[70:73], v[146:149], v[224:227], v[70:73]
	v_mfma_f32_16x16x32_bf16 v[58:61], v[130:133], v[232:235], v[58:61]
	v_mfma_f32_16x16x32_bf16 v[54:57], v[146:149], v[232:235], v[54:57]
	v_mfma_f32_16x16x32_bf16 v[42:45], v[130:133], v[240:243], v[42:45]
	v_mfma_f32_16x16x32_bf16 v[38:41], v[146:149], v[240:243], v[38:41]
	v_mfma_f32_16x16x32_bf16 v[22:25], v[130:133], v[248:251], v[22:25]
	v_mfma_f32_16x16x32_bf16 v[18:21], v[146:149], v[248:251], v[18:21]
	v_mfma_f32_16x16x32_bf16 v[50:53], v[164:167], v[220:223], v[50:53]
	v_mfma_f32_16x16x32_bf16 v[46:49], v[208:211], v[220:223], v[46:49]
	v_mfma_f32_16x16x32_bf16 v[34:37], v[164:167], v[228:231], v[34:37]
	v_mfma_f32_16x16x32_bf16 v[30:33], v[208:211], v[228:231], v[30:33]
	v_mfma_f32_16x16x32_bf16 v[26:29], v[164:167], v[236:239], v[26:29]
	v_mfma_f32_16x16x32_bf16 v[2:5], v[208:211], v[236:239], v[2:5]
	v_mfma_f32_16x16x32_bf16 v[12:15], v[164:167], v[244:247], v[12:15]
	v_mfma_f32_16x16x32_bf16 v[6:9], v[208:211], v[244:247], v[8:11]
	v_mfma_f32_16x16x32_bf16 v[50:53], v[204:207], v[224:227], v[50:53]
	v_mfma_f32_16x16x32_bf16 v[46:49], v[216:219], v[224:227], v[46:49]
	v_mfma_f32_16x16x32_bf16 v[34:37], v[204:207], v[232:235], v[34:37]
	v_mfma_f32_16x16x32_bf16 v[30:33], v[216:219], v[232:235], v[30:33]
	v_mfma_f32_16x16x32_bf16 v[26:29], v[204:207], v[240:243], v[26:29]
	v_mfma_f32_16x16x32_bf16 v[2:5], v[216:219], v[240:243], v[2:5]
	v_mfma_f32_16x16x32_bf16 v[12:15], v[204:207], v[248:251], v[12:15]
	v_mfma_f32_16x16x32_bf16 v[6:9], v[216:219], v[248:251], v[6:9]
	s_barrier
	s_add_i32 s53, 0, 0x18000
	v_add_u32_e32 v10, s53, v170
	s_add_i32 s54, 0, 0x1c000
	ds_read_b128 v[126:129], v10
	ds_read_b128 v[130:133], v10 offset:1024
	ds_read_b128 v[142:145], v10 offset:2048
	ds_read_b128 v[146:149], v10 offset:3072
	v_add_u32_e32 v10, s54, v170
	ds_read_b128 v[164:167], v10
	ds_read_b128 v[204:207], v10 offset:1024
	ds_read_b128 v[208:211], v10 offset:2048
	ds_read_b128 v[216:219], v10 offset:3072
	s_add_u32 s22, s22, 0x80000
	s_addc_u32 s23, s23, 0
	s_mov_b32 m0, s40
	v_lshl_add_u64 v[10:11], s[22:23], 0, v[150:151]
	ds_read_b128 v[220:223], v196 offset:32768
	ds_read_b128 v[224:227], v196 offset:33792
	ds_read_b128 v[228:231], v196 offset:34816
	ds_read_b128 v[232:235], v196 offset:35840
	ds_read_b128 v[236:239], v196 offset:36864
	ds_read_b128 v[240:243], v196 offset:37888
	ds_read_b128 v[244:247], v196 offset:38912
	ds_read_b128 v[248:251], v196 offset:39936
	global_load_lds_dwordx4 v[10:11], off
	v_lshl_add_u64 v[10:11], s[22:23], 0, v[152:153]
	s_mov_b32 m0, s41
	s_nop 0
	global_load_lds_dwordx4 v[10:11], off
	s_waitcnt vmcnt(8) lgkmcnt(0)
	s_barrier
	v_mfma_f32_16x16x32_bf16 v[138:141], v[126:129], v[220:223], v[138:141]
	v_mfma_f32_16x16x32_bf16 v[134:137], v[142:145], v[220:223], v[134:137]
	v_mfma_f32_16x16x32_bf16 v[122:125], v[126:129], v[228:231], v[122:125]
	v_mfma_f32_16x16x32_bf16 v[118:121], v[142:145], v[228:231], v[118:121]
	v_mfma_f32_16x16x32_bf16 v[106:109], v[126:129], v[236:239], v[106:109]
	v_mfma_f32_16x16x32_bf16 v[102:105], v[142:145], v[236:239], v[102:105]
	v_mfma_f32_16x16x32_bf16 v[90:93], v[126:129], v[244:247], v[90:93]
	v_mfma_f32_16x16x32_bf16 v[86:89], v[142:145], v[244:247], v[86:89]
	v_mfma_f32_16x16x32_bf16 v[138:141], v[130:133], v[224:227], v[138:141]
	v_mfma_f32_16x16x32_bf16 v[134:137], v[146:149], v[224:227], v[134:137]
	v_mfma_f32_16x16x32_bf16 v[122:125], v[130:133], v[232:235], v[122:125]
	v_mfma_f32_16x16x32_bf16 v[118:121], v[146:149], v[232:235], v[118:121]
	v_mfma_f32_16x16x32_bf16 v[106:109], v[130:133], v[240:243], v[106:109]
	v_mfma_f32_16x16x32_bf16 v[102:105], v[146:149], v[240:243], v[102:105]
	v_mfma_f32_16x16x32_bf16 v[90:93], v[130:133], v[248:251], v[90:93]
	v_mfma_f32_16x16x32_bf16 v[86:89], v[146:149], v[248:251], v[86:89]
	v_mfma_f32_16x16x32_bf16 v[114:117], v[164:167], v[220:223], v[114:117]
	v_mfma_f32_16x16x32_bf16 v[110:113], v[208:211], v[220:223], v[110:113]
	v_mfma_f32_16x16x32_bf16 v[98:101], v[164:167], v[228:231], v[98:101]
	v_mfma_f32_16x16x32_bf16 v[94:97], v[208:211], v[228:231], v[94:97]
	v_mfma_f32_16x16x32_bf16 v[82:85], v[164:167], v[236:239], v[82:85]
	v_mfma_f32_16x16x32_bf16 v[78:81], v[208:211], v[236:239], v[78:81]
	v_mfma_f32_16x16x32_bf16 v[66:69], v[164:167], v[244:247], v[66:69]
	v_mfma_f32_16x16x32_bf16 v[62:65], v[208:211], v[244:247], v[62:65]
	v_mfma_f32_16x16x32_bf16 v[114:117], v[204:207], v[224:227], v[114:117]
	v_mfma_f32_16x16x32_bf16 v[110:113], v[216:219], v[224:227], v[110:113]
	v_mfma_f32_16x16x32_bf16 v[98:101], v[204:207], v[232:235], v[98:101]
	v_mfma_f32_16x16x32_bf16 v[94:97], v[216:219], v[232:235], v[94:97]
	v_mfma_f32_16x16x32_bf16 v[82:85], v[204:207], v[240:243], v[82:85]
	v_mfma_f32_16x16x32_bf16 v[78:81], v[216:219], v[240:243], v[78:81]
	v_mfma_f32_16x16x32_bf16 v[66:69], v[204:207], v[248:251], v[66:69]
	v_mfma_f32_16x16x32_bf16 v[62:65], v[216:219], v[248:251], v[62:65]
	s_barrier
	s_add_i32 s22, s53, s17
	v_lshl_add_u64 v[10:11], v[168:169], 0, s[36:37]
	s_mov_b32 m0, s22
	ds_read_b128 v[220:223], v196 offset:49152
	ds_read_b128 v[224:227], v196 offset:50176
	ds_read_b128 v[228:231], v196 offset:51200
	ds_read_b128 v[232:235], v196 offset:52224
	ds_read_b128 v[236:239], v196 offset:53248
	ds_read_b128 v[240:243], v196 offset:54272
	ds_read_b128 v[244:247], v196 offset:55296
	ds_read_b128 v[248:251], v196 offset:56320
	global_load_lds_dwordx4 v[10:11], off
	s_add_i32 m0, s22, 0x2000
	s_add_u32 s20, s20, 0x80080
	v_lshl_add_u64 v[10:11], v[198:199], 0, s[36:37]
	s_addc_u32 s21, s21, 0
	s_add_i32 s22, s54, s17
	global_load_lds_dwordx4 v[10:11], off
	v_lshl_add_u64 v[10:11], s[20:21], 0, v[0:1]
	s_mov_b32 m0, s22
	s_nop 0
	global_load_lds_dwordx4 v[10:11], off
	v_lshl_add_u64 v[10:11], s[20:21], 0, v[154:155]
	s_add_i32 m0, s22, 0x2000
	s_nop 0
	global_load_lds_dwordx4 v[10:11], off
	v_lshl_add_u64 v[10:11], v[200:201], 0, s[36:37]
	s_mov_b32 m0, s2
	s_nop 0
	global_load_lds_dwordx4 v[10:11], off
	v_lshl_add_u64 v[10:11], v[202:203], 0, s[36:37]
	s_mov_b32 m0, s3
	s_nop 0
	global_load_lds_dwordx4 v[10:11], off
	s_add_i32 s52, s52, 2
	s_add_u32 s8, s8, 0x100
	s_addc_u32 s9, s9, 0
	s_add_u32 s50, s50, 0x100
	s_addc_u32 s51, s51, 0
	s_cmp_gt_u32 s52, 29
	s_waitcnt vmcnt(8) lgkmcnt(0)
	s_barrier
	v_mfma_f32_16x16x32_bf16 v[74:77], v[126:129], v[220:223], v[74:77]
	v_mfma_f32_16x16x32_bf16 v[70:73], v[142:145], v[220:223], v[70:73]
	v_mfma_f32_16x16x32_bf16 v[58:61], v[126:129], v[228:231], v[58:61]
	v_mfma_f32_16x16x32_bf16 v[54:57], v[142:145], v[228:231], v[54:57]
	v_mfma_f32_16x16x32_bf16 v[42:45], v[126:129], v[236:239], v[42:45]
	v_mfma_f32_16x16x32_bf16 v[38:41], v[142:145], v[236:239], v[38:41]
	v_mfma_f32_16x16x32_bf16 v[22:25], v[126:129], v[244:247], v[22:25]
	v_mfma_f32_16x16x32_bf16 v[18:21], v[142:145], v[244:247], v[18:21]
	v_mfma_f32_16x16x32_bf16 v[74:77], v[130:133], v[224:227], v[74:77]
	v_mfma_f32_16x16x32_bf16 v[70:73], v[146:149], v[224:227], v[70:73]
	v_mfma_f32_16x16x32_bf16 v[58:61], v[130:133], v[232:235], v[58:61]
	v_mfma_f32_16x16x32_bf16 v[54:57], v[146:149], v[232:235], v[54:57]
	v_mfma_f32_16x16x32_bf16 v[42:45], v[130:133], v[240:243], v[42:45]
	v_mfma_f32_16x16x32_bf16 v[38:41], v[146:149], v[240:243], v[38:41]
	v_mfma_f32_16x16x32_bf16 v[22:25], v[130:133], v[248:251], v[22:25]
	v_mfma_f32_16x16x32_bf16 v[18:21], v[146:149], v[248:251], v[18:21]
	v_mfma_f32_16x16x32_bf16 v[50:53], v[164:167], v[220:223], v[50:53]
	v_mfma_f32_16x16x32_bf16 v[46:49], v[208:211], v[220:223], v[46:49]
	v_mfma_f32_16x16x32_bf16 v[34:37], v[164:167], v[228:231], v[34:37]
	v_mfma_f32_16x16x32_bf16 v[30:33], v[208:211], v[228:231], v[30:33]
	v_mfma_f32_16x16x32_bf16 v[26:29], v[164:167], v[236:239], v[26:29]
	v_mfma_f32_16x16x32_bf16 v[2:5], v[208:211], v[236:239], v[2:5]
	v_mfma_f32_16x16x32_bf16 v[10:13], v[164:167], v[244:247], v[12:15]
	v_mfma_f32_16x16x32_bf16 v[6:9], v[208:211], v[244:247], v[6:9]
	v_mfma_f32_16x16x32_bf16 v[50:53], v[204:207], v[224:227], v[50:53]
	v_mfma_f32_16x16x32_bf16 v[46:49], v[216:219], v[224:227], v[46:49]
	v_mfma_f32_16x16x32_bf16 v[34:37], v[204:207], v[232:235], v[34:37]
	v_mfma_f32_16x16x32_bf16 v[30:33], v[216:219], v[232:235], v[30:33]
	v_mfma_f32_16x16x32_bf16 v[26:29], v[204:207], v[240:243], v[26:29]
	v_mfma_f32_16x16x32_bf16 v[2:5], v[216:219], v[240:243], v[2:5]
	v_mfma_f32_16x16x32_bf16 v[12:15], v[204:207], v[248:251], v[10:13]
	v_mfma_f32_16x16x32_bf16 v[8:11], v[216:219], v[248:251], v[6:9]
	s_barrier
	s_cbranch_scc0 .LBB0_878
	s_and_b64 vcc, exec, s[74:75]
	s_cbranch_vccz .LBB0_881
	s_barrier
